# prologue / in-proj-tail weight-conversion split at 12288 items = exactly 6 items per wave in the prologue
# baseline (speedup 1.0000x reference)
; #define LAS __attribute__((address_space(3)))
;     __device__ __forceinline__ bf16* Win_t() const { return (bf16*)(ws + WS_WIN); }
; __device__ __forceinline__ P0Item p0_decode(Frame& F, int it, int n4) {
;     constexpr int I_IN = (D / 64) * (NP1 / 64), I_OUT = (D / 64) * (D / 64), I_GU = (D / 64) * (2 * FF / 64);
;     P0Item q; int r = it;
;     if (r < I_IN) { const int nblk = NP1 / 64, kb = r / nblk, nb = r % nblk, n = nb * 64 + n4;
;         const int sc = n < SRC_GLR ? n : n + GRANK;
;         q.srcp = F.w_in + sc; q.ldw = DIN; q.kscale = F.norm1_w; q.K = D; q.WT = F.Win_t(); q.n0 = nb * 64; q.k0 = kb * 64; return q; }
; template <bool NT> __device__ __forceinline__ void p0_items(Frame& F, int it0, int it1, int gw, int nw) {
;     LAS unsigned char* scr = F.lds + F.wave * 16384;
;     const int n4 = (F.lane & 15) * 4, kr = F.lane >> 4;
;     f32x4 va[16], vb[16]; P0Item A, B; int it = it0 + gw;
;     if (it < it1) { A = p0_decode(F, it, n4); p0_load(A, kr, va); }
.LBB0_16:
	s_add_u32 s4, s54, 0x4000000
	s_addc_u32 s5, s55, 0
	v_lshlrev_b32_e32 v2, 2, v183
	s_add_u32 s6, s56, 0xa00000
	v_and_b32_e32 v141, 60, v2
	s_addc_u32 s7, s57, 0
	s_add_u32 s18, s56, 0x2800000
	v_and_b32_e32 v142, 28, v2
	v_mov_b32_e32 v2, s93
	v_mov_b32_e32 v3, s91
	v_cmp_gt_u32_e32 vcc, 32, v141
	v_lshrrev_b32_e32 v1, 4, v183
	s_addc_u32 s19, s57, 0
	v_cndmask_b32_e32 v135, v2, v3, vcc
	v_mov_b32_e32 v2, s92
	v_mov_b32_e32 v3, s90
	s_cmpk_gt_i32 s16, 0x2fff
	v_cndmask_b32_e32 v134, v2, v3, vcc
	v_or_b32_e32 v143, 4, v1
	v_or_b32_e32 v145, 8, v1
	v_or_b32_e32 v146, 12, v1
	v_or_b32_e32 v147, 16, v1
	v_or_b32_e32 v148, 20, v1
	v_or_b32_e32 v149, 24, v1
	v_or_b32_e32 v150, 28, v1
	v_or_b32_e32 v151, 32, v1
	v_or_b32_e32 v152, 36, v1
	v_or_b32_e32 v153, 40, v1
	v_or_b32_e32 v154, 44, v1
	v_or_b32_e32 v155, 48, v1
	v_or_b32_e32 v156, 52, v1
	v_or_b32_e32 v157, 56, v1
	v_or_b32_e32 v158, 60, v1
	s_cbranch_scc1 .LBB0_19
	s_mul_hi_i32 s1, s16, 0x51eb851f
	s_lshr_b32 s8, s1, 31
	s_ashr_i32 s1, s1, 6
	s_add_i32 s1, s1, s8
	s_mul_i32 s8, s1, 0xc8
	s_sub_i32 s8, s16, s8
	s_lshl_b32 s17, s8, 6
	v_or_b32_e32 v2, s17, v141
	s_movk_i32 s8, 0x1a00
	s_cmpk_lt_i32 s16, 0x1900
	v_cmp_gt_i32_e32 vcc, s8, v2
	s_cbranch_scc1 .LBB0_20
	s_cmpk_lt_u32 s16, 0x1d00
	s_cselect_b64 vcc, -1, 0
	s_add_i32 s1, s16, 0xe300
	s_and_b32 s8, s1, 0xffff
	s_mul_i32 s8, s8, 0xba2f
	s_lshr_b32 s8, s8, 23
	s_mul_i32 s9, s8, 0xb0
	s_sub_i32 s1, s1, s9
	s_and_b32 s1, s1, 0xffff
	s_lshl_b32 s10, s1, 5
	s_and_b32 s10, s10, 0x60
	s_lshl_b32 s9, s1, 6
	v_or_b32_e32 v4, s10, v142
	s_lshl_b32 s1, s1, 7
	s_and_b32 s10, s0, 0x7c0
	s_and_b32 s20, s1, 0x7e00
	s_mov_b32 s21, 0
	s_lshl_b32 s8, s8, 6
	s_lshl_b32 s0, s10, 2
	v_lshl_add_u64 v[2:3], v[134:135], 0, s[20:21]
	v_lshlrev_b32_e32 v4, 2, v4
	v_mov_b32_e32 v5, 0
	s_add_u32 s0, s50, s0
	v_lshl_add_u64 v[2:3], v[2:3], 0, v[4:5]
	s_addc_u32 s1, s51, 0
	v_lshlrev_b32_e32 v4, 2, v141
	v_lshl_add_u64 v[4:5], s[0:1], 0, v[4:5]
	s_lshl_b32 s0, s16, 1
	s_and_b32 s0, s0, 0x3fc0
	s_add_i32 s11, s0, 0xffffce00
	s_and_b64 s[0:1], vcc, exec
	s_movk_i32 s0, 0x800
	v_cndmask_b32_e32 v27, v3, v5, vcc
	v_cndmask_b32_e32 v26, v2, v4, vcc
	s_cselect_b32 s23, 0, s89
	s_cselect_b32 s22, 0, s88
	s_cselect_b32 s25, s7, s5
	s_cselect_b32 s24, s6, s4
	s_cselect_b32 s20, s0, 0x1600
	s_cselect_b32 s17, s10, s9
	s_cselect_b32 s63, s11, s8
	s_branch .LBB0_21

;     __device__ __forceinline__ bf16* Win_t() const { return (bf16*)(ws + WS_WIN); }
; __device__ __forceinline__ P0Item p0_decode(Frame& F, int it, int n4) {
;     constexpr int I_IN = (D / 64) * (NP1 / 64), I_OUT = (D / 64) * (D / 64), I_GU = (D / 64) * (2 * FF / 64);
;     P0Item q; int r = it;
;     if (r < I_IN) { const int nblk = NP1 / 64, kb = r / nblk, nb = r % nblk, n = nb * 64 + n4;
;         const int sc = n < SRC_GLR ? n : n + GRANK;
;         q.srcp = F.w_in + sc; q.ldw = DIN; q.kscale = F.norm1_w; q.K = D; q.WT = F.Win_t(); q.n0 = nb * 64; q.k0 = kb * 64; return q; }
; template <bool NT> __device__ __forceinline__ void p0_items(Frame& F, int it0, int it1, int gw, int nw) {
;     ...
;     while (it < it1) {
;         int itn = it + nw;
;         if (itn < it1) { B = p0_decode(F, itn, n4); p0_load(B, kr, vb); }
;         p0_finish<NT>(A, va, scr, F.lane);
;         it = itn; if (it >= it1) break;
;         itn = it + nw;
;         if (itn < it1) { A = p0_decode(F, itn, n4); p0_load(A, kr, va); }
.LBB0_57:
	s_cmpk_gt_i32 s65, 0x2fff
	s_mov_b64 s[34:35], -1
	s_cbranch_scc1 .LBB0_56
	s_add_i32 s65, s65, s20
	s_cmpk_lt_i32 s65, 0x3000
	s_cselect_b64 s[68:69], -1, 0
	s_cmpk_gt_i32 s65, 0x2fff
	s_cselect_b64 s[34:35], -1, 0
	s_and_b64 vcc, exec, s[34:35]
	s_cbranch_vccnz .LBB0_100
	s_cmpk_gt_i32 s65, 0x18ff
	s_cbranch_scc0 .LBB0_62
	s_cmpk_gt_u32 s65, 0x1cff
	s_cbranch_scc0 .LBB0_63
	s_add_i32 s0, s65, 0xe300
	s_and_b32 s1, s0, 0xffff
	s_mul_i32 s1, s1, 0xba2f
	s_lshr_b32 s1, s1, 23
	s_mul_i32 s8, s1, 0xb0
	s_sub_i32 s0, s0, s8
	s_and_b32 s0, s0, 0xffff
	s_lshl_b32 s8, s0, 5
	s_lshl_b32 s67, s0, 6
	s_and_b32 s8, s8, 0x60
	s_lshl_b32 s0, s0, 7
	v_or_b32_e32 v27, s8, v142
	s_and_b32 s26, s0, 0x7e00
	v_lshl_add_u64 v[28:29], v[134:135], 0, s[26:27]
	v_lshlrev_b32_e32 v46, 2, v27
	v_mov_b32_e32 v47, v26
	v_lshl_add_u64 v[138:139], v[28:29], 0, v[46:47]
	s_lshl_b32 s74, s1, 6
	s_mov_b64 s[28:29], s[88:89]
	s_mov_b64 s[70:71], 0x1600
	s_mov_b64 s[30:31], s[4:5]
	s_cbranch_execz .LBB0_64
	s_branch .LBB0_65

; #define GAS __attribute__((address_space(1)))
; #define LAS __attribute__((address_space(3)))
; #define LDS_WAIT() asm volatile("s_waitcnt lgkmcnt(0)" ::: "memory")
; __device__ __forceinline__ s16x4_t tr_read(LAS const unsigned char* p) { return __builtin_bit_cast(s16x4_t, __builtin_amdgcn_ds_read_tr16_b64_v4i16((LAS s16x4_t*)p)); }
; __device__ __forceinline__ bf16x8_t cat8(s16x4_t lo, s16x4_t hi) { return __builtin_shufflevector(lo, hi, 0, 1, 2, 3, 4, 5, 6, 7); }
; template <bool NT> __device__ __forceinline__ void p0_finish(const P0Item& q, f32x4 (&v)[16], LAS unsigned char* scr, int lane) {
;     constexpr int RS = 144;
;     const int kr = lane >> 4, n4 = (lane & 15) * 4;
;     if (q.kscale) {
; #pragma unroll
;         for (int i = 0; i < 16; ++i) v[i] = v[i] * q.kscale[q.k0 + 4 * i + kr];
;     }
; #pragma unroll
;     for (int i = 0; i < 16; ++i) { v2u w; w.x = cvtpk(v[i][0], v[i][1]); w.y = cvtpk(v[i][2], v[i][3]); *(LAS v2u*)(scr + (4 * i + kr) * RS + n4 * 2) = w; }
;     const int G = lane >> 4, i16 = lane & 15, qq = i16 >> 2, p = i16 & 3;
; #pragma unroll
;     for (int ng = 0; ng < 4; ++ng)
; #pragma unroll
;         for (int u = 0; u < 2; ++u) { const LAS unsigned char* rp = scr + (8 * (G + 4 * u) + qq) * RS + (16 * ng + 4 * p) * 2;
;             const bf16x8_t t = cat8(tr_read(rp), tr_read(rp + 4 * RS));
;             *(GAS bf16x8_t*)(q.WT + pg8::blk_off_b(q.n0 + 16 * ng + i16, q.k0 + 8 * (G + 4 * u), q.K)) = t; }
;     LDS_WAIT(); asm volatile("" ::: "memory");
; }
.LBB0_102:
	s_waitcnt vmcnt(0)
	v_cvt_pk_bf16_f32 v28, v2, v3
	v_cvt_pk_bf16_f32 v29, v4, v5
	v_cvt_pk_bf16_f32 v138, v6, v7
	v_cvt_pk_bf16_f32 v139, v8, v9
	ds_write2_b64 v165, v[28:29], v[138:139] offset1:72
	v_cvt_pk_bf16_f32 v28, v10, v11
	v_cvt_pk_bf16_f32 v29, v12, v13
	v_cvt_pk_bf16_f32 v138, v14, v15
	v_cvt_pk_bf16_f32 v139, v16, v17
	ds_write2_b64 v165, v[28:29], v[138:139] offset0:144 offset1:216
	v_cvt_pk_bf16_f32 v28, v18, v19
	v_cvt_pk_bf16_f32 v29, v20, v21
	v_cvt_pk_bf16_f32 v138, v22, v23
	v_cvt_pk_bf16_f32 v139, v24, v25
	v_add_u32_e32 v168, 0x800, v165
	ds_write2_b64 v168, v[28:29], v[138:139] offset0:32 offset1:104
	v_cvt_pk_bf16_f32 v28, v30, v31
	v_cvt_pk_bf16_f32 v29, v32, v33
	v_cvt_pk_bf16_f32 v138, v34, v35
	v_cvt_pk_bf16_f32 v139, v36, v37
	ds_write2_b64 v168, v[28:29], v[138:139] offset0:176 offset1:248
	v_cvt_pk_bf16_f32 v28, v38, v39
	v_cvt_pk_bf16_f32 v29, v40, v41
	v_cvt_pk_bf16_f32 v138, v42, v43
	v_cvt_pk_bf16_f32 v139, v44, v45
	v_add_u32_e32 v169, 0x1000, v165
	ds_write2_b64 v169, v[28:29], v[138:139] offset0:64 offset1:136
	v_cvt_pk_bf16_f32 v28, v50, v51
	v_cvt_pk_bf16_f32 v29, v52, v53
	v_cvt_pk_bf16_f32 v138, v58, v59
	v_cvt_pk_bf16_f32 v139, v60, v61
	v_add_u32_e32 v170, 0x1400, v165
	ds_write2_b64 v170, v[28:29], v[138:139] offset0:80 offset1:152
	v_cvt_pk_bf16_f32 v28, v74, v75
	v_cvt_pk_bf16_f32 v29, v76, v77
	v_cvt_pk_bf16_f32 v138, v82, v83
	v_cvt_pk_bf16_f32 v139, v84, v85
	v_add_u32_e32 v171, 0x1800, v165
	ds_write2_b64 v171, v[28:29], v[138:139] offset0:96 offset1:168
	v_cvt_pk_bf16_f32 v28, v94, v95
	v_cvt_pk_bf16_f32 v29, v96, v97
	v_cvt_pk_bf16_f32 v138, v102, v103
	v_cvt_pk_bf16_f32 v139, v104, v105
	v_add_u32_e32 v172, 0x1c00, v165
	v_add_u32_e32 v27, s17, v140
	ds_write2_b64 v172, v[28:29], v[138:139] offset0:112 offset1:184
	v_lshlrev_b32_e32 v28, 2, v27
	v_and_b32_e32 v28, 16, v28
	v_lshrrev_b32_e32 v29, 1, v27
	v_add_u32_e32 v138, s63, v160
	v_and_or_b32 v173, v29, s21, v28
	v_ashrrev_i32_e32 v28, 3, v27
	v_and_b32_e32 v139, 3, v27
	v_and_b32_e32 v182, 0xffffffe0, v28
	v_ashrrev_i32_e32 v204, 6, v138
	v_and_or_b32 v139, v29, 12, v139
	v_add_u32_e32 v28, v182, v204
	ds_read_b64_tr_b16 v[176:177], v166 offset:576
	v_ashrrev_i32_e32 v29, 31, v28
	v_lshlrev_b32_e32 v192, 5, v139
	v_and_b32_e32 v206, 31, v138
	v_and_b32_e32 v193, 16, v27
	v_lshrrev_b32_e32 v173, 3, v173
	v_bfe_u32 v205, v138, 5, 1
	v_bitop3_b32 v175, v192, v193, v206 bitop3:0x36
	v_lshlrev_b64 v[28:29], 15, v[28:29]
	v_lshlrev_b32_e32 v27, 9, v27
	v_or_b32_e32 v174, v173, v205
	v_lshl_add_u64 v[28:29], s[24:25], 0, v[28:29]
	v_and_b32_e32 v138, 0x4000, v27
	v_mov_b32_e32 v139, v26
	v_lshlrev_b32_e32 v27, 1, v175
	v_lshl_add_u64 v[28:29], v[28:29], 0, v[138:139]
	v_lshl_or_b32 v174, v174, 10, v27
	v_mov_b32_e32 v175, v26
	v_add_u32_e32 v27, s63, v161
	v_lshl_add_u64 v[28:29], v[28:29], 0, v[174:175]
	v_ashrrev_i32_e32 v207, 6, v27
	ds_read_b64_tr_b16 v[174:175], v166
	ds_read_b64_tr_b16 v[178:179], v166 offset:32
	ds_read_b64_tr_b16 v[184:185], v166 offset:64
	ds_read_b64_tr_b16 v[188:189], v166 offset:96
	ds_read_b64_tr_b16 v[180:181], v166 offset:608
	ds_read_b64_tr_b16 v[186:187], v166 offset:640
	ds_read_b64_tr_b16 v[190:191], v166 offset:672
	s_waitcnt lgkmcnt(6)
	global_store_dwordx4 v[28:29], v[174:177], off
	v_add_u32_e32 v28, v182, v207
	v_ashrrev_i32_e32 v29, 31, v28
	ds_read_b64_tr_b16 v[176:177], v167 offset:576
	v_bfe_u32 v182, v27, 5, 1
	v_and_b32_e32 v27, 31, v27
	v_lshlrev_b64 v[28:29], 15, v[28:29]
	v_bitop3_b32 v174, v192, v193, v27 bitop3:0x36
	v_lshl_add_u64 v[28:29], s[24:25], 0, v[28:29]
	v_or_b32_e32 v173, v173, v182
	v_lshl_add_u64 v[28:29], v[28:29], 0, v[138:139]
	v_lshlrev_b32_e32 v138, 1, v174
	v_lshl_or_b32 v138, v173, 10, v138
	v_lshl_add_u64 v[28:29], v[28:29], 0, v[138:139]
	v_add_u32_e32 v138, s17, v162
	ds_read_b64_tr_b16 v[174:175], v167
	ds_read_b64_tr_b16 v[192:193], v167 offset:32
	ds_read_b64_tr_b16 v[196:197], v167 offset:64
	ds_read_b64_tr_b16 v[200:201], v167 offset:96
	ds_read_b64_tr_b16 v[194:195], v167 offset:608
	ds_read_b64_tr_b16 v[198:199], v167 offset:640
	ds_read_b64_tr_b16 v[202:203], v167 offset:672
	s_waitcnt lgkmcnt(6)
; #define GAS __attribute__((address_space(1)))
; #define LAS __attribute__((address_space(3)))
; #define LDS_WAIT() asm volatile("s_waitcnt lgkmcnt(0)" ::: "memory")
; __device__ __forceinline__ s16x4_t tr_read(LAS const unsigned char* p) { return __builtin_bit_cast(s16x4_t, __builtin_amdgcn_ds_read_tr16_b64_v4i16((LAS s16x4_t*)p)); }
; __device__ __forceinline__ bf16x8_t cat8(s16x4_t lo, s16x4_t hi) { return __builtin_shufflevector(lo, hi, 0, 1, 2, 3, 4, 5, 6, 7); }
; template <bool NT> __device__ __forceinline__ void p0_finish(const P0Item& q, f32x4 (&v)[16], LAS unsigned char* scr, int lane) {
;     ...
;     for (int i = 0; i < 16; ++i) { v2u w; w.x = cvtpk(v[i][0], v[i][1]); w.y = cvtpk(v[i][2], v[i][3]); *(LAS v2u*)(scr + (4 * i + kr) * RS + n4 * 2) = w; }
;     const int G = lane >> 4, i16 = lane & 15, qq = i16 >> 2, p = i16 & 3;
; #pragma unroll
;     for (int ng = 0; ng < 4; ++ng)
; #pragma unroll
;         for (int u = 0; u < 2; ++u) { const LAS unsigned char* rp = scr + (8 * (G + 4 * u) + qq) * RS + (16 * ng + 4 * p) * 2;
;             const bf16x8_t t = cat8(tr_read(rp), tr_read(rp + 4 * RS));
;             *(GAS bf16x8_t*)(q.WT + pg8::blk_off_b(q.n0 + 16 * ng + i16, q.k0 + 8 * (G + 4 * u), q.K)) = t; }
;     LDS_WAIT(); asm volatile("" ::: "memory");
; }
; template <bool NT> __device__ __forceinline__ void p0_items(Frame& F, int it0, int it1, int gw, int nw) {
;     ...
;         it = itn; if (it >= it1) break;
;         itn = it + nw;
;         if (itn < it1) { A = p0_decode(F, itn, n4); p0_load(A, kr, va); }
	global_store_dwordx4 v[28:29], v[174:177], off
	v_lshlrev_b32_e32 v28, 2, v138
	v_and_b32_e32 v28, 16, v28
	v_lshrrev_b32_e32 v29, 1, v138
	v_and_or_b32 v173, v29, s21, v28
	v_ashrrev_i32_e32 v28, 3, v138
	v_and_b32_e32 v139, 3, v138
	v_and_b32_e32 v176, 0xffffffe0, v28
	v_and_or_b32 v139, v29, 12, v139
	v_add_u32_e32 v28, v176, v204
	v_ashrrev_i32_e32 v29, 31, v28
	v_lshlrev_b32_e32 v177, 5, v139
	v_and_b32_e32 v208, 16, v138
	v_lshrrev_b32_e32 v173, 3, v173
	v_bitop3_b32 v175, v177, v208, v206 bitop3:0x36
	v_lshlrev_b64 v[28:29], 15, v[28:29]
	v_lshlrev_b32_e32 v138, 9, v138
	v_or_b32_e32 v174, v173, v205
	v_lshl_add_u64 v[28:29], s[24:25], 0, v[28:29]
	v_and_b32_e32 v138, 0x4000, v138
	v_mov_b32_e32 v139, v26
	v_lshlrev_b32_e32 v175, 1, v175
	v_lshl_add_u64 v[28:29], v[28:29], 0, v[138:139]
	v_lshl_or_b32 v174, v174, 10, v175
	v_mov_b32_e32 v175, v26
	v_lshl_add_u64 v[28:29], v[28:29], 0, v[174:175]
	global_store_dwordx4 v[28:29], v[178:181], off
	v_add_u32_e32 v28, v176, v207
	v_ashrrev_i32_e32 v29, 31, v28
	v_lshlrev_b64 v[28:29], 15, v[28:29]
	v_bitop3_b32 v174, v177, v208, v27 bitop3:0x36
	v_lshl_add_u64 v[28:29], s[24:25], 0, v[28:29]
	v_or_b32_e32 v173, v173, v182
	v_lshl_add_u64 v[28:29], v[28:29], 0, v[138:139]
	v_lshlrev_b32_e32 v138, 1, v174
	v_lshl_or_b32 v138, v173, 10, v138
	v_lshl_add_u64 v[28:29], v[28:29], 0, v[138:139]
	v_add_u32_e32 v138, s17, v163
	s_waitcnt lgkmcnt(2)
	global_store_dwordx4 v[28:29], v[192:195], off
	v_lshlrev_b32_e32 v28, 2, v138
	v_and_b32_e32 v28, 16, v28
	v_lshrrev_b32_e32 v29, 1, v138
	v_and_or_b32 v173, v29, s21, v28
	v_ashrrev_i32_e32 v28, 3, v138
	v_and_b32_e32 v139, 3, v138
	v_and_b32_e32 v176, 0xffffffe0, v28
	v_and_or_b32 v139, v29, 12, v139
	v_add_u32_e32 v28, v176, v204
	v_ashrrev_i32_e32 v29, 31, v28
	v_lshlrev_b32_e32 v177, 5, v139
	v_and_b32_e32 v178, 16, v138
	v_lshrrev_b32_e32 v173, 3, v173
	v_bitop3_b32 v175, v177, v178, v206 bitop3:0x36
	v_lshlrev_b64 v[28:29], 15, v[28:29]
	v_lshlrev_b32_e32 v138, 9, v138
	v_or_b32_e32 v174, v173, v205
	v_lshl_add_u64 v[28:29], s[24:25], 0, v[28:29]
	v_and_b32_e32 v138, 0x4000, v138
	v_mov_b32_e32 v139, v26
	v_lshlrev_b32_e32 v175, 1, v175
	v_lshl_add_u64 v[28:29], v[28:29], 0, v[138:139]
	v_lshl_or_b32 v174, v174, 10, v175
	v_mov_b32_e32 v175, v26
	v_lshl_add_u64 v[28:29], v[28:29], 0, v[174:175]
	global_store_dwordx4 v[28:29], v[184:187], off
	v_add_u32_e32 v28, v176, v207
	v_ashrrev_i32_e32 v29, 31, v28
	v_lshlrev_b64 v[28:29], 15, v[28:29]
	v_bitop3_b32 v174, v177, v178, v27 bitop3:0x36
	v_lshl_add_u64 v[28:29], s[24:25], 0, v[28:29]
	v_or_b32_e32 v173, v173, v182
	v_lshl_add_u64 v[28:29], v[28:29], 0, v[138:139]
	v_lshlrev_b32_e32 v138, 1, v174
	v_lshl_or_b32 v138, v173, 10, v138
	v_lshl_add_u64 v[28:29], v[28:29], 0, v[138:139]
	v_add_u32_e32 v138, s17, v164
	s_waitcnt lgkmcnt(1)
	global_store_dwordx4 v[28:29], v[196:199], off
	v_lshlrev_b32_e32 v28, 2, v138
	v_and_b32_e32 v28, 16, v28
	v_lshrrev_b32_e32 v29, 1, v138
	v_and_or_b32 v173, v29, s21, v28
	v_ashrrev_i32_e32 v28, 3, v138
	v_and_b32_e32 v139, 3, v138
	v_and_b32_e32 v176, 0xffffffe0, v28
	v_and_or_b32 v139, v29, 12, v139
	v_add_u32_e32 v28, v176, v204
	v_ashrrev_i32_e32 v29, 31, v28
	v_lshlrev_b32_e32 v177, 5, v139
	v_and_b32_e32 v178, 16, v138
	v_lshrrev_b32_e32 v173, 3, v173
	v_bitop3_b32 v175, v177, v178, v206 bitop3:0x36
	v_lshlrev_b64 v[28:29], 15, v[28:29]
	v_lshlrev_b32_e32 v138, 9, v138
	v_or_b32_e32 v174, v173, v205
	v_lshl_add_u64 v[28:29], s[24:25], 0, v[28:29]
	v_and_b32_e32 v138, 0x4000, v138
	v_mov_b32_e32 v139, v26
	v_lshlrev_b32_e32 v175, 1, v175
	v_lshl_add_u64 v[28:29], v[28:29], 0, v[138:139]
	v_lshl_or_b32 v174, v174, 10, v175
	v_mov_b32_e32 v175, v26
	v_lshl_add_u64 v[28:29], v[28:29], 0, v[174:175]
	global_store_dwordx4 v[28:29], v[188:191], off
	v_add_u32_e32 v28, v176, v207
	v_ashrrev_i32_e32 v29, 31, v28
	v_bitop3_b32 v27, v177, v178, v27 bitop3:0x36
	v_lshlrev_b64 v[28:29], 15, v[28:29]
	v_or_b32_e32 v173, v173, v182
	v_lshl_add_u64 v[28:29], s[24:25], 0, v[28:29]
	v_lshlrev_b32_e32 v27, 1, v27
	v_lshl_add_u64 v[28:29], v[28:29], 0, v[138:139]
	v_lshl_or_b32 v138, v173, 10, v27
	v_lshl_add_u64 v[28:29], v[28:29], 0, v[138:139]
	s_waitcnt lgkmcnt(0)
	global_store_dwordx4 v[28:29], v[200:203], off
	s_waitcnt lgkmcnt(0)
	s_andn2_b64 vcc, exec, s[68:69]
	s_cbranch_vccnz .LBB0_56
	s_add_i32 s65, s65, s20
	s_cmpk_gt_i32 s65, 0x2fff
	s_cbranch_scc1 .LBB0_145
	s_cmpk_gt_i32 s65, 0x18ff
	s_cbranch_scc0 .LBB0_107
	s_cmpk_gt_u32 s65, 0x1cff
	s_cbranch_scc0 .LBB0_108
	s_add_i32 s0, s65, 0xe300
	s_and_b32 s1, s0, 0xffff
	s_mul_i32 s1, s1, 0xba2f
	s_lshr_b32 s1, s1, 23
	s_mul_i32 s8, s1, 0xb0
	s_sub_i32 s0, s0, s8
	s_and_b32 s0, s0, 0xffff
	s_lshl_b32 s8, s0, 5
	s_lshl_b32 s17, s0, 6
	s_and_b32 s8, s8, 0x60
	s_lshl_b32 s0, s0, 7
	v_or_b32_e32 v4, s8, v142
	s_and_b32 s26, s0, 0x7e00
	v_lshl_add_u64 v[2:3], v[134:135], 0, s[26:27]
	v_lshlrev_b32_e32 v4, 2, v4
	v_mov_b32_e32 v5, v26
	v_lshl_add_u64 v[138:139], v[2:3], 0, v[4:5]
	s_lshl_b32 s63, s1, 6
	s_mov_b64 s[22:23], s[88:89]
	s_mov_b64 s[68:69], 0x1600
	s_mov_b64 s[24:25], s[4:5]
	s_cbranch_execz .LBB0_109
	s_branch .LBB0_110

; #define LAS __attribute__((address_space(3)))
; template <bool NT> __device__ __forceinline__ void p0_items(Frame& F, int it0, int it1, int gw, int nw) {
;     LAS unsigned char* scr = F.lds + F.wave * 16384;
;     const int n4 = (F.lane & 15) * 4, kr = F.lane >> 4;
;     f32x4 va[16], vb[16]; P0Item A, B; int it = it0 + gw;
;     if (it < it1) { A = p0_decode(F, it, n4); p0_load(A, kr, va); }
; __global__ void __launch_bounds__(NTHREADS, 2) hybrid_fwd(Args args) {
;     ...
;             constexpr int NT = (M / 256) * (NP1 / 256); const int nshort = F.G - (NT % F.G), first_short = NT % F.G;
;             if ((NT % F.G) != 0 && (int)blockIdx.x >= first_short) { const int sw = ((int)blockIdx.x - first_short) * NWAVES + F.wave;
;                 p1_glr(F, sw, nshort * NWAVES); p0_items<true>(F, P0_NITEMS - P0_DEFER_ITEMS, P0_NITEMS, sw, nshort * NWAVES); }
.LBB0_228:
	v_lshlrev_b32_e32 v20, 2, v183
	s_add_i32 s67, s0, 0x3000
	v_and_b32_e32 v142, 60, v20
	s_cmpk_gt_i32 s0, 0x11f7
	v_lshrrev_b32_e32 v143, 4, v183
	s_cbranch_scc1 .LBB0_233
	s_cmpk_gt_i32 s0, 0xecf7
	s_cbranch_scc0 .LBB0_234
	s_cmpk_gt_u32 s67, 0x1cff
	s_cbranch_scc0 .LBB0_235
	s_cmpk_gt_u32 s67, 0x32ff
	s_cbranch_scc0 .LBB0_236
	s_lshl_b32 s0, s67, 6
	s_and_b32 s64, s0, 0x7c0
	s_lshl_b32 s0, s64, 2
	s_add_u32 s0, s94, s0
	s_addc_u32 s1, s95, 0
	v_lshlrev_b32_e32 v2, 2, v142
	v_mov_b32_e32 v3, 0
	s_add_u32 s18, s56, 0x1200000
	v_lshl_add_u64 v[18:19], s[0:1], 0, v[2:3]
	s_addc_u32 s19, s57, 0
	s_lshl_b32 s0, s67, 1
	s_and_b32 s0, s0, 0x7fffffc0
	s_add_i32 s65, s0, 0xffff9a00
	s_mov_b64 s[20:21], 0
	s_mov_b64 s[6:7], 0
	s_branch .LBB0_237

; #define LAS __attribute__((address_space(3)))
; template <bool NT> __device__ __forceinline__ void p0_items(Frame& F, int it0, int it1, int gw, int nw) {
;     LAS unsigned char* scr = F.lds + F.wave * 16384;
;     const int n4 = (F.lane & 15) * 4, kr = F.lane >> 4;
;     f32x4 va[16], vb[16]; P0Item A, B; int it = it0 + gw;
;     if (it < it1) { A = p0_decode(F, it, n4); p0_load(A, kr, va); }
; __global__ void __launch_bounds__(NTHREADS, 2) hybrid_fwd(Args args) {
;     ...
;             constexpr int NT = (M / 256) * (NP1 / 256); const int nshort = F.G - (NT % F.G), first_short = NT % F.G;
;             if ((NT % F.G) != 0 && (int)blockIdx.x >= first_short) { const int sw = ((int)blockIdx.x - first_short) * NWAVES + F.wave;
;                 p1_glr(F, sw, nshort * NWAVES); p0_items<true>(F, P0_NITEMS - P0_DEFER_ITEMS, P0_NITEMS, sw, nshort * NWAVES); }
.LBB0_399:
	v_lshlrev_b32_e32 v20, 2, v183
	s_add_i32 s35, s0, 0x3000
	v_and_b32_e32 v142, 60, v20
	s_cmpk_gt_i32 s0, 0x11f7
	v_lshrrev_b32_e32 v143, 4, v183
	s_cbranch_scc1 .LBB0_421
	s_cmpk_gt_i32 s0, 0xecf7
	s_cbranch_scc0 .LBB0_439
	s_cmpk_gt_u32 s35, 0x1cff
	s_cbranch_scc0 .LBB0_912
	s_cmpk_gt_u32 s35, 0x32ff
	s_cbranch_scc0 .LBB0_913
	s_lshl_b32 s0, s35, 6
	s_and_b32 s36, s0, 0x7c0
	s_lshl_b32 s0, s36, 2
	s_add_u32 s0, s94, s0
	s_addc_u32 s1, s95, 0
	s_waitcnt vmcnt(0)
	v_lshlrev_b32_e32 v2, 2, v142
	v_mov_b32_e32 v3, 0
	s_add_u32 s6, s56, 0x1200000
	v_lshl_add_u64 v[18:19], s[0:1], 0, v[2:3]
	s_addc_u32 s7, s57, 0
	s_lshl_b32 s0, s35, 1
	s_and_b32 s0, s0, 0x7fffffc0
	s_add_i32 s37, s0, 0xffff9a00
	s_mov_b64 s[18:19], 0
	s_mov_b64 s[4:5], 0
	s_branch .LBB0_914
